# transpose items: 32 row loads in flight + batched LDS reads (4 copies)
# baseline (speedup 1.0000x reference)
.LBB0_18:
	s_ashr_i32 s9, s8, 31
	s_lshl_b64 s[8:9], s[8:9], 3
	s_add_u32 s10, s0, s8
	s_addc_u32 s11, s1, s9
	s_lshr_b32 s8, s13, 5
	v_cvt_f32_u32_e32 v10, s8
	s_load_dwordx2 s[28:29], s[10:11], 0x0
	s_sub_i32 s10, 0, s8
	s_abs_i32 s25, s15
	v_rcp_iflag_f32_e32 v10, v10
	s_ashr_i32 s19, s15, 31
	s_mov_b32 s9, 0
	s_mov_b32 s14, 1
	v_mul_f32_e32 v10, 0x4f7ffffe, v10
	v_cvt_u32_f32_e32 v10, v10
	s_nop 0
	v_readfirstlane_b32 s11, v10
	s_mul_i32 s10, s10, s11
	s_mul_hi_u32 s10, s11, s10
	s_add_i32 s11, s11, s10
	s_mul_hi_u32 s10, s25, s11
	s_mul_i32 s11, s10, s8
	s_sub_i32 s11, s25, s11
	s_add_i32 s34, s10, 1
	s_sub_i32 s25, s11, s8
	s_cmp_ge_u32 s11, s8
	s_cselect_b32 s10, s34, s10
	s_cselect_b32 s11, s25, s11
	s_add_i32 s25, s10, 1
	s_cmp_ge_u32 s11, s8
	s_cselect_b32 s10, s25, s10
	s_xor_b32 s10, s10, s19
	s_sub_i32 s10, s10, s19
	s_mul_i32 s8, s10, s8
	s_sub_i32 s11, s15, s8
	s_lshl_b32 s8, s10, 6
	s_lshl_b32 s10, s11, 5
	s_ashr_i32 s11, s10, 31
	s_lshl_b64 s[34:35], s[10:11], 2
	s_waitcnt lgkmcnt(0)
	s_add_u32 s28, s28, s34
	s_addc_u32 s29, s29, s35
	s_mul_i32 s70, s8, s13
	s_lshl_b32 s71, s13, 2
	s_lshl_b32 s70, s70, 2
	s_add_u32 s28, s28, s70
	s_addc_u32 s29, s29, 0
	v_mad_u32_u24 v210, v2, s71, v4
	v_mad_u32_u24 v211, v2, s3, v6
	s_lshl_b32 s71, s71, 1
	global_load_dword v166, v210, s[28:29]
	s_add_u32 s28, s28, s71
	s_addc_u32 s29, s29, 0
	global_load_dword v167, v210, s[28:29]
	s_add_u32 s28, s28, s71
	s_addc_u32 s29, s29, 0
	global_load_dword v168, v210, s[28:29]
	s_add_u32 s28, s28, s71
	s_addc_u32 s29, s29, 0
	global_load_dword v169, v210, s[28:29]
	s_add_u32 s28, s28, s71
	s_addc_u32 s29, s29, 0
	global_load_dword v170, v210, s[28:29]
	s_add_u32 s28, s28, s71
	s_addc_u32 s29, s29, 0
	global_load_dword v171, v210, s[28:29]
	s_add_u32 s28, s28, s71
	s_addc_u32 s29, s29, 0
	global_load_dword v172, v210, s[28:29]
	s_add_u32 s28, s28, s71
	s_addc_u32 s29, s29, 0
	global_load_dword v173, v210, s[28:29]
	s_add_u32 s28, s28, s71
	s_addc_u32 s29, s29, 0
	global_load_dword v174, v210, s[28:29]
	s_add_u32 s28, s28, s71
	s_addc_u32 s29, s29, 0
	global_load_dword v175, v210, s[28:29]
	s_add_u32 s28, s28, s71
	s_addc_u32 s29, s29, 0
	global_load_dword v176, v210, s[28:29]
	s_add_u32 s28, s28, s71
	s_addc_u32 s29, s29, 0
	global_load_dword v177, v210, s[28:29]
	s_add_u32 s28, s28, s71
	s_addc_u32 s29, s29, 0
	global_load_dword v178, v210, s[28:29]
	s_add_u32 s28, s28, s71
	s_addc_u32 s29, s29, 0
	global_load_dword v179, v210, s[28:29]
	s_add_u32 s28, s28, s71
	s_addc_u32 s29, s29, 0
	global_load_dword v180, v210, s[28:29]
	s_add_u32 s28, s28, s71
	s_addc_u32 s29, s29, 0
	global_load_dword v181, v210, s[28:29]
	s_add_u32 s28, s28, s71
	s_addc_u32 s29, s29, 0
	global_load_dword v182, v210, s[28:29]
	s_add_u32 s28, s28, s71
	s_addc_u32 s29, s29, 0
	global_load_dword v183, v210, s[28:29]
	s_add_u32 s28, s28, s71
	s_addc_u32 s29, s29, 0
	global_load_dword v184, v210, s[28:29]
	s_add_u32 s28, s28, s71
	s_addc_u32 s29, s29, 0
	global_load_dword v185, v210, s[28:29]
	s_add_u32 s28, s28, s71
	s_addc_u32 s29, s29, 0
	global_load_dword v186, v210, s[28:29]
	s_add_u32 s28, s28, s71
	s_addc_u32 s29, s29, 0
	global_load_dword v187, v210, s[28:29]
	s_add_u32 s28, s28, s71
	s_addc_u32 s29, s29, 0
	global_load_dword v188, v210, s[28:29]
	s_add_u32 s28, s28, s71
	s_addc_u32 s29, s29, 0
	global_load_dword v189, v210, s[28:29]
	s_add_u32 s28, s28, s71
	s_addc_u32 s29, s29, 0
	global_load_dword v190, v210, s[28:29]
	s_add_u32 s28, s28, s71
	s_addc_u32 s29, s29, 0
	global_load_dword v191, v210, s[28:29]
	s_add_u32 s28, s28, s71
	s_addc_u32 s29, s29, 0
	global_load_dword v192, v210, s[28:29]
	s_add_u32 s28, s28, s71
	s_addc_u32 s29, s29, 0
	global_load_dword v193, v210, s[28:29]
	s_add_u32 s28, s28, s71
	s_addc_u32 s29, s29, 0
	global_load_dword v194, v210, s[28:29]
	s_add_u32 s28, s28, s71
	s_addc_u32 s29, s29, 0
	global_load_dword v195, v210, s[28:29]
	s_add_u32 s28, s28, s71
	s_addc_u32 s29, s29, 0
	global_load_dword v198, v210, s[28:29]
	s_add_u32 s28, s28, s71
	s_addc_u32 s29, s29, 0
	global_load_dword v199, v210, s[28:29]
	s_waitcnt vmcnt(31)
	ds_write_b32 v211, v166
	s_waitcnt vmcnt(30)
	ds_write_b32 v211, v167 offset:264
	s_waitcnt vmcnt(29)
	ds_write_b32 v211, v168 offset:528
	s_waitcnt vmcnt(28)
	ds_write_b32 v211, v169 offset:792
	s_waitcnt vmcnt(27)
	ds_write_b32 v211, v170 offset:1056
	s_waitcnt vmcnt(26)
	ds_write_b32 v211, v171 offset:1320
	s_waitcnt vmcnt(25)
	ds_write_b32 v211, v172 offset:1584
	s_waitcnt vmcnt(24)
	ds_write_b32 v211, v173 offset:1848
	s_waitcnt vmcnt(23)
	ds_write_b32 v211, v174 offset:2112
	s_waitcnt vmcnt(22)
	ds_write_b32 v211, v175 offset:2376
	s_waitcnt vmcnt(21)
	ds_write_b32 v211, v176 offset:2640
	s_waitcnt vmcnt(20)
	ds_write_b32 v211, v177 offset:2904
	s_waitcnt vmcnt(19)
	ds_write_b32 v211, v178 offset:3168
	s_waitcnt vmcnt(18)
	ds_write_b32 v211, v179 offset:3432
	s_waitcnt vmcnt(17)
	ds_write_b32 v211, v180 offset:3696
	s_waitcnt vmcnt(16)
	ds_write_b32 v211, v181 offset:3960
	s_waitcnt vmcnt(15)
	ds_write_b32 v211, v182 offset:4224
	s_waitcnt vmcnt(14)
	ds_write_b32 v211, v183 offset:4488
	s_waitcnt vmcnt(13)
	ds_write_b32 v211, v184 offset:4752
	s_waitcnt vmcnt(12)
	ds_write_b32 v211, v185 offset:5016
	s_waitcnt vmcnt(11)
	ds_write_b32 v211, v186 offset:5280
	s_waitcnt vmcnt(10)
	ds_write_b32 v211, v187 offset:5544
	s_waitcnt vmcnt(9)
	ds_write_b32 v211, v188 offset:5808
	s_waitcnt vmcnt(8)
	ds_write_b32 v211, v189 offset:6072
	s_waitcnt vmcnt(7)
	ds_write_b32 v211, v190 offset:6336
	s_waitcnt vmcnt(6)
	ds_write_b32 v211, v191 offset:6600
	s_waitcnt vmcnt(5)
	ds_write_b32 v211, v192 offset:6864
	s_waitcnt vmcnt(4)
	ds_write_b32 v211, v193 offset:7128
	s_waitcnt vmcnt(3)
	ds_write_b32 v211, v194 offset:7392
	s_waitcnt vmcnt(2)
	ds_write_b32 v211, v195 offset:7656
	s_waitcnt vmcnt(1)
	ds_write_b32 v211, v198 offset:7920
	s_waitcnt vmcnt(0)
	ds_write_b32 v211, v199 offset:8184
	s_waitcnt lgkmcnt(0)
	s_add_i32 s10, s10, s12
	v_add_u32_e32 v22, s10, v3
	ds_read2_b32 v[166:167], v7 offset1:33
	ds_read2_b32 v[168:169], v7 offset0:66 offset1:99
	ds_read2_b32 v[170:171], v7 offset0:132 offset1:165
	ds_read2_b32 v[172:173], v7 offset0:198 offset1:231
	ds_read2_b32 v[174:175], v7 offset0:8 offset1:41
	ds_read2_b32 v[176:177], v7 offset0:74 offset1:107
	ds_read2_b32 v[178:179], v7 offset0:140 offset1:173
	ds_read2_b32 v[180:181], v7 offset0:206 offset1:239
	ds_read2_b32 v[182:183], v7 offset0:16 offset1:49
	ds_read2_b32 v[184:185], v7 offset0:82 offset1:115
	ds_read2_b32 v[186:187], v7 offset0:148 offset1:181
	ds_read2_b32 v[188:189], v7 offset0:214 offset1:247
	ds_read2_b32 v[190:191], v7 offset0:24 offset1:57
	ds_read2_b32 v[192:193], v7 offset0:90 offset1:123
	ds_read2_b32 v[194:195], v7 offset0:156 offset1:189
	ds_read2_b32 v[198:199], v7 offset0:222 offset1:255
	s_ashr_i32 s9, s8, 31
	v_ashrrev_i32_e32 v23, 31, v22
	s_waitcnt lgkmcnt(12)
	v_cvt_pk_bf16_f32 v16, v166, v167
	v_lshl_add_u64 v[20:21], s[8:9], 1, v[8:9]
	v_lshlrev_b64 v[22:23], 12, v[22:23]
	s_waitcnt lgkmcnt(12)
	v_cvt_pk_bf16_f32 v17, v168, v169
	v_lshl_add_u64 v[22:23], v[20:21], 0, v[22:23]
	s_waitcnt lgkmcnt(12)
	v_cvt_pk_bf16_f32 v18, v170, v171
	s_waitcnt lgkmcnt(12)
	v_cvt_pk_bf16_f32 v19, v172, v173
	global_store_dwordx4 v[22:23], v[16:19], off
	s_nop 1
	v_add_u32_e32 v22, s10, v12
	v_ashrrev_i32_e32 v23, 31, v22
	s_waitcnt lgkmcnt(8)
	v_cvt_pk_bf16_f32 v16, v174, v175
	v_lshlrev_b64 v[22:23], 12, v[22:23]
	s_waitcnt lgkmcnt(8)
	v_cvt_pk_bf16_f32 v17, v176, v177
	v_lshl_add_u64 v[22:23], v[20:21], 0, v[22:23]
	s_waitcnt lgkmcnt(8)
	v_cvt_pk_bf16_f32 v18, v178, v179
	s_waitcnt lgkmcnt(8)
	v_cvt_pk_bf16_f32 v19, v180, v181
	global_store_dwordx4 v[22:23], v[16:19], off
	s_nop 1
	v_add_u32_e32 v22, s10, v13
	v_ashrrev_i32_e32 v23, 31, v22
	s_waitcnt lgkmcnt(4)
	v_cvt_pk_bf16_f32 v16, v182, v183
	v_lshlrev_b64 v[22:23], 12, v[22:23]
	s_waitcnt lgkmcnt(4)
	v_cvt_pk_bf16_f32 v17, v184, v185
	v_lshl_add_u64 v[22:23], v[20:21], 0, v[22:23]
	s_waitcnt lgkmcnt(4)
	v_cvt_pk_bf16_f32 v18, v186, v187
	s_waitcnt lgkmcnt(4)
	v_cvt_pk_bf16_f32 v19, v188, v189
	global_store_dwordx4 v[22:23], v[16:19], off
	s_nop 1
	v_add_u32_e32 v22, s10, v14
	v_ashrrev_i32_e32 v23, 31, v22
	s_waitcnt lgkmcnt(0)
	v_cvt_pk_bf16_f32 v16, v190, v191
	v_lshlrev_b64 v[22:23], 12, v[22:23]
	s_waitcnt lgkmcnt(0)
	v_cvt_pk_bf16_f32 v17, v192, v193
	v_lshl_add_u64 v[20:21], v[20:21], 0, v[22:23]
	s_waitcnt lgkmcnt(0)
	v_cvt_pk_bf16_f32 v18, v194, v195
	s_waitcnt lgkmcnt(0)
	v_cvt_pk_bf16_f32 v19, v198, v199
	global_store_dwordx4 v[20:21], v[16:19], off
	s_nop 1
	s_waitcnt lgkmcnt(0)
	s_add_i32 s5, s5, s18
	s_cmpk_gt_i32 s5, 0x33ff
	s_cbranch_scc0 .LBB0_7
	s_branch .LBB0_22

.LBB0_271:
	s_ashr_i32 s9, s8, 31
	s_lshl_b64 s[8:9], s[8:9], 3
	s_add_u32 s10, s0, s8
	s_addc_u32 s11, s1, s9
	s_lshr_b32 s8, s38, 5
	v_cvt_f32_u32_e32 v8, s8
	s_load_dwordx2 s[40:41], s[10:11], 0x0
	s_sub_i32 s10, 0, s8
	s_abs_i32 s13, s29
	v_rcp_iflag_f32_e32 v8, v8
	s_ashr_i32 s12, s29, 31
	s_mov_b32 s9, 0
	s_mov_b32 s39, 1
	v_mul_f32_e32 v8, 0x4f7ffffe, v8
	v_cvt_u32_f32_e32 v8, v8
	s_nop 0
	v_readfirstlane_b32 s11, v8
	s_mul_i32 s10, s10, s11
	s_mul_hi_u32 s10, s11, s10
	s_add_i32 s11, s11, s10
	s_mul_hi_u32 s10, s13, s11
	s_mul_i32 s11, s10, s8
	s_sub_i32 s11, s13, s11
	s_add_i32 s42, s10, 1
	s_sub_i32 s13, s11, s8
	s_cmp_ge_u32 s11, s8
	s_cselect_b32 s10, s42, s10
	s_cselect_b32 s11, s13, s11
	s_add_i32 s13, s10, 1
	s_cmp_ge_u32 s11, s8
	s_cselect_b32 s10, s13, s10
	s_xor_b32 s10, s10, s12
	s_sub_i32 s10, s10, s12
	s_mul_i32 s8, s10, s8
	s_sub_i32 s11, s29, s8
	s_lshl_b32 s8, s10, 6
	s_lshl_b32 s10, s11, 5
	s_ashr_i32 s11, s10, 31
	s_lshl_b64 s[42:43], s[10:11], 2
	s_waitcnt lgkmcnt(0)
	s_add_u32 s40, s40, s42
	s_addc_u32 s41, s41, s43
	s_mul_i32 s70, s8, s38
	s_lshl_b32 s71, s38, 2
	s_lshl_b32 s70, s70, 2
	s_add_u32 s40, s40, s70
	s_addc_u32 s41, s41, 0
	v_mad_u32_u24 v210, v0, s71, v2
	v_mad_u32_u24 v211, v0, s15, v4
	s_lshl_b32 s71, s71, 1
	global_load_dword v166, v210, s[40:41]
	s_add_u32 s40, s40, s71
	s_addc_u32 s41, s41, 0
	global_load_dword v167, v210, s[40:41]
	s_add_u32 s40, s40, s71
	s_addc_u32 s41, s41, 0
	global_load_dword v168, v210, s[40:41]
	s_add_u32 s40, s40, s71
	s_addc_u32 s41, s41, 0
	global_load_dword v169, v210, s[40:41]
	s_add_u32 s40, s40, s71
	s_addc_u32 s41, s41, 0
	global_load_dword v170, v210, s[40:41]
	s_add_u32 s40, s40, s71
	s_addc_u32 s41, s41, 0
	global_load_dword v171, v210, s[40:41]
	s_add_u32 s40, s40, s71
	s_addc_u32 s41, s41, 0
	global_load_dword v172, v210, s[40:41]
	s_add_u32 s40, s40, s71
	s_addc_u32 s41, s41, 0
	global_load_dword v173, v210, s[40:41]
	s_add_u32 s40, s40, s71
	s_addc_u32 s41, s41, 0
	global_load_dword v174, v210, s[40:41]
	s_add_u32 s40, s40, s71
	s_addc_u32 s41, s41, 0
	global_load_dword v175, v210, s[40:41]
	s_add_u32 s40, s40, s71
	s_addc_u32 s41, s41, 0
	global_load_dword v176, v210, s[40:41]
	s_add_u32 s40, s40, s71
	s_addc_u32 s41, s41, 0
	global_load_dword v177, v210, s[40:41]
	s_add_u32 s40, s40, s71
	s_addc_u32 s41, s41, 0
	global_load_dword v178, v210, s[40:41]
	s_add_u32 s40, s40, s71
	s_addc_u32 s41, s41, 0
	global_load_dword v179, v210, s[40:41]
	s_add_u32 s40, s40, s71
	s_addc_u32 s41, s41, 0
	global_load_dword v180, v210, s[40:41]
	s_add_u32 s40, s40, s71
	s_addc_u32 s41, s41, 0
	global_load_dword v181, v210, s[40:41]
	s_add_u32 s40, s40, s71
	s_addc_u32 s41, s41, 0
	global_load_dword v182, v210, s[40:41]
	s_add_u32 s40, s40, s71
	s_addc_u32 s41, s41, 0
	global_load_dword v183, v210, s[40:41]
	s_add_u32 s40, s40, s71
	s_addc_u32 s41, s41, 0
	global_load_dword v184, v210, s[40:41]
	s_add_u32 s40, s40, s71
	s_addc_u32 s41, s41, 0
	global_load_dword v185, v210, s[40:41]
	s_add_u32 s40, s40, s71
	s_addc_u32 s41, s41, 0
	global_load_dword v186, v210, s[40:41]
	s_add_u32 s40, s40, s71
	s_addc_u32 s41, s41, 0
	global_load_dword v187, v210, s[40:41]
	s_add_u32 s40, s40, s71
	s_addc_u32 s41, s41, 0
	global_load_dword v188, v210, s[40:41]
	s_add_u32 s40, s40, s71
	s_addc_u32 s41, s41, 0
	global_load_dword v189, v210, s[40:41]
	s_add_u32 s40, s40, s71
	s_addc_u32 s41, s41, 0
	global_load_dword v190, v210, s[40:41]
	s_add_u32 s40, s40, s71
	s_addc_u32 s41, s41, 0
	global_load_dword v191, v210, s[40:41]
	s_add_u32 s40, s40, s71
	s_addc_u32 s41, s41, 0
	global_load_dword v192, v210, s[40:41]
	s_add_u32 s40, s40, s71
	s_addc_u32 s41, s41, 0
	global_load_dword v193, v210, s[40:41]
	s_add_u32 s40, s40, s71
	s_addc_u32 s41, s41, 0
	global_load_dword v194, v210, s[40:41]
	s_add_u32 s40, s40, s71
	s_addc_u32 s41, s41, 0
	global_load_dword v195, v210, s[40:41]
	s_add_u32 s40, s40, s71
	s_addc_u32 s41, s41, 0
	global_load_dword v198, v210, s[40:41]
	s_add_u32 s40, s40, s71
	s_addc_u32 s41, s41, 0
	global_load_dword v199, v210, s[40:41]
	s_waitcnt vmcnt(31)
	ds_write_b32 v211, v166
	s_waitcnt vmcnt(30)
	ds_write_b32 v211, v167 offset:264
	s_waitcnt vmcnt(29)
	ds_write_b32 v211, v168 offset:528
	s_waitcnt vmcnt(28)
	ds_write_b32 v211, v169 offset:792
	s_waitcnt vmcnt(27)
	ds_write_b32 v211, v170 offset:1056
	s_waitcnt vmcnt(26)
	ds_write_b32 v211, v171 offset:1320
	s_waitcnt vmcnt(25)
	ds_write_b32 v211, v172 offset:1584
	s_waitcnt vmcnt(24)
	ds_write_b32 v211, v173 offset:1848
	s_waitcnt vmcnt(23)
	ds_write_b32 v211, v174 offset:2112
	s_waitcnt vmcnt(22)
	ds_write_b32 v211, v175 offset:2376
	s_waitcnt vmcnt(21)
	ds_write_b32 v211, v176 offset:2640
	s_waitcnt vmcnt(20)
	ds_write_b32 v211, v177 offset:2904
	s_waitcnt vmcnt(19)
	ds_write_b32 v211, v178 offset:3168
	s_waitcnt vmcnt(18)
	ds_write_b32 v211, v179 offset:3432
	s_waitcnt vmcnt(17)
	ds_write_b32 v211, v180 offset:3696
	s_waitcnt vmcnt(16)
	ds_write_b32 v211, v181 offset:3960
	s_waitcnt vmcnt(15)
	ds_write_b32 v211, v182 offset:4224
	s_waitcnt vmcnt(14)
	ds_write_b32 v211, v183 offset:4488
	s_waitcnt vmcnt(13)
	ds_write_b32 v211, v184 offset:4752
	s_waitcnt vmcnt(12)
	ds_write_b32 v211, v185 offset:5016
	s_waitcnt vmcnt(11)
	ds_write_b32 v211, v186 offset:5280
	s_waitcnt vmcnt(10)
	ds_write_b32 v211, v187 offset:5544
	s_waitcnt vmcnt(9)
	ds_write_b32 v211, v188 offset:5808
	s_waitcnt vmcnt(8)
	ds_write_b32 v211, v189 offset:6072
	s_waitcnt vmcnt(7)
	ds_write_b32 v211, v190 offset:6336
	s_waitcnt vmcnt(6)
	ds_write_b32 v211, v191 offset:6600
	s_waitcnt vmcnt(5)
	ds_write_b32 v211, v192 offset:6864
	s_waitcnt vmcnt(4)
	ds_write_b32 v211, v193 offset:7128
	s_waitcnt vmcnt(3)
	ds_write_b32 v211, v194 offset:7392
	s_waitcnt vmcnt(2)
	ds_write_b32 v211, v195 offset:7656
	s_waitcnt vmcnt(1)
	ds_write_b32 v211, v198 offset:7920
	s_waitcnt vmcnt(0)
	ds_write_b32 v211, v199 offset:8184
	s_add_u32 s6, s34, s6
	s_waitcnt lgkmcnt(0)
	s_addc_u32 s7, s35, s7
	s_add_i32 s10, s10, s25
	s_lshl_b64 s[4:5], s[4:5], 1
	s_add_u32 s6, s6, s4
	ds_read2_b32 v[166:167], v10 offset1:33
	ds_read2_b32 v[168:169], v10 offset0:66 offset1:99
	ds_read2_b32 v[170:171], v10 offset0:132 offset1:165
	ds_read2_b32 v[172:173], v10 offset0:198 offset1:231
	ds_read2_b32 v[174:175], v10 offset0:8 offset1:41
	ds_read2_b32 v[176:177], v10 offset0:74 offset1:107
	ds_read2_b32 v[178:179], v10 offset0:140 offset1:173
	ds_read2_b32 v[180:181], v10 offset0:206 offset1:239
	ds_read2_b32 v[182:183], v10 offset0:16 offset1:49
	ds_read2_b32 v[184:185], v10 offset0:82 offset1:115
	ds_read2_b32 v[186:187], v10 offset0:148 offset1:181
	ds_read2_b32 v[188:189], v10 offset0:214 offset1:247
	ds_read2_b32 v[190:191], v10 offset0:24 offset1:57
	ds_read2_b32 v[192:193], v10 offset0:90 offset1:123
	ds_read2_b32 v[194:195], v10 offset0:156 offset1:189
	ds_read2_b32 v[198:199], v10 offset0:222 offset1:255
	s_addc_u32 s7, s7, s5
	s_ashr_i32 s9, s8, 31
	s_waitcnt lgkmcnt(12)
	v_cvt_pk_bf16_f32 v14, v166, v167
	s_lshl_b64 s[4:5], s[8:9], 1
	s_waitcnt lgkmcnt(12)
	v_cvt_pk_bf16_f32 v15, v168, v169
	v_add_u32_e32 v18, s10, v5
	s_add_u32 s4, s6, s4
	v_ashrrev_i32_e32 v19, 31, v18
	s_waitcnt lgkmcnt(12)
	v_cvt_pk_bf16_f32 v16, v170, v171
	s_addc_u32 s5, s7, s5
	v_lshl_add_u64 v[20:21], s[4:5], 0, v[6:7]
	s_waitcnt lgkmcnt(12)
	v_cvt_pk_bf16_f32 v17, v172, v173
	v_lshlrev_b64 v[8:9], 12, v[18:19]
	v_lshl_add_u64 v[8:9], v[20:21], 0, v[8:9]
	global_store_dwordx4 v[8:9], v[14:17], off
	s_nop 1
	v_add_u32_e32 v18, s10, v11
	v_ashrrev_i32_e32 v19, 31, v18
	s_waitcnt lgkmcnt(8)
	v_cvt_pk_bf16_f32 v14, v174, v175
	v_lshlrev_b64 v[18:19], 12, v[18:19]
	s_waitcnt lgkmcnt(8)
	v_cvt_pk_bf16_f32 v15, v176, v177
	v_lshl_add_u64 v[18:19], v[20:21], 0, v[18:19]
	s_waitcnt lgkmcnt(8)
	v_cvt_pk_bf16_f32 v16, v178, v179
	s_waitcnt lgkmcnt(8)
	v_cvt_pk_bf16_f32 v17, v180, v181
	global_store_dwordx4 v[18:19], v[14:17], off
	s_nop 1
	v_add_u32_e32 v18, s10, v12
	v_ashrrev_i32_e32 v19, 31, v18
	s_waitcnt lgkmcnt(4)
	v_cvt_pk_bf16_f32 v14, v182, v183
	v_lshlrev_b64 v[18:19], 12, v[18:19]
	s_waitcnt lgkmcnt(4)
	v_cvt_pk_bf16_f32 v15, v184, v185
	v_lshl_add_u64 v[18:19], v[20:21], 0, v[18:19]
	s_waitcnt lgkmcnt(4)
	v_cvt_pk_bf16_f32 v16, v186, v187
	s_waitcnt lgkmcnt(4)
	v_cvt_pk_bf16_f32 v17, v188, v189
	global_store_dwordx4 v[18:19], v[14:17], off
	s_nop 1
	v_add_u32_e32 v18, s10, v13
	v_ashrrev_i32_e32 v19, 31, v18
	s_waitcnt lgkmcnt(0)
	v_cvt_pk_bf16_f32 v14, v190, v191
	v_lshlrev_b64 v[18:19], 12, v[18:19]
	s_waitcnt lgkmcnt(0)
	v_cvt_pk_bf16_f32 v15, v192, v193
	v_lshl_add_u64 v[18:19], v[20:21], 0, v[18:19]
	s_waitcnt lgkmcnt(0)
	v_cvt_pk_bf16_f32 v16, v194, v195
	s_waitcnt lgkmcnt(0)
	v_cvt_pk_bf16_f32 v17, v198, v199
	global_store_dwordx4 v[18:19], v[14:17], off
	s_nop 1
	s_waitcnt lgkmcnt(0)
	s_add_i32 s3, s3, s14
	s_cmpk_lt_i32 s3, 0x5400
	s_cbranch_scc1 .LBB0_240
	s_branch .LBB0_275

.LBB0_490:
	s_ashr_i32 s9, s8, 31
	s_lshl_b64 s[8:9], s[8:9], 3
	s_add_u32 s10, s0, s8
	s_addc_u32 s11, s1, s9
	s_lshr_b32 s8, s19, 5
	v_cvt_f32_u32_e32 v8, s8
	s_load_dwordx2 s[40:41], s[10:11], 0x0
	s_sub_i32 s10, 0, s8
	s_abs_i32 s13, s29
	v_rcp_iflag_f32_e32 v8, v8
	s_ashr_i32 s12, s29, 31
	s_mov_b32 s9, 0
	s_mov_b32 s38, 1
	v_mul_f32_e32 v8, 0x4f7ffffe, v8
	v_cvt_u32_f32_e32 v8, v8
	s_nop 0
	v_readfirstlane_b32 s11, v8
	s_mul_i32 s10, s10, s11
	s_mul_hi_u32 s10, s11, s10
	s_add_i32 s11, s11, s10
	s_mul_hi_u32 s10, s13, s11
	s_mul_i32 s11, s10, s8
	s_sub_i32 s11, s13, s11
	s_add_i32 s39, s10, 1
	s_sub_i32 s13, s11, s8
	s_cmp_ge_u32 s11, s8
	s_cselect_b32 s10, s39, s10
	s_cselect_b32 s11, s13, s11
	s_add_i32 s13, s10, 1
	s_cmp_ge_u32 s11, s8
	s_cselect_b32 s10, s13, s10
	s_xor_b32 s10, s10, s12
	s_sub_i32 s10, s10, s12
	s_mul_i32 s8, s10, s8
	s_sub_i32 s11, s29, s8
	s_lshl_b32 s8, s10, 6
	s_lshl_b32 s10, s11, 5
	s_ashr_i32 s11, s10, 31
	s_lshl_b64 s[42:43], s[10:11], 2
	s_waitcnt lgkmcnt(0)
	s_add_u32 s40, s40, s42
	s_addc_u32 s41, s41, s43
	s_mul_i32 s70, s8, s19
	s_lshl_b32 s71, s19, 2
	s_lshl_b32 s70, s70, 2
	s_add_u32 s40, s40, s70
	s_addc_u32 s41, s41, 0
	v_mad_u32_u24 v210, v0, s71, v6
	v_mad_u32_u24 v211, v0, s15, v4
	s_lshl_b32 s71, s71, 1
	global_load_dword v166, v210, s[40:41]
	s_add_u32 s40, s40, s71
	s_addc_u32 s41, s41, 0
	global_load_dword v167, v210, s[40:41]
	s_add_u32 s40, s40, s71
	s_addc_u32 s41, s41, 0
	global_load_dword v168, v210, s[40:41]
	s_add_u32 s40, s40, s71
	s_addc_u32 s41, s41, 0
	global_load_dword v169, v210, s[40:41]
	s_add_u32 s40, s40, s71
	s_addc_u32 s41, s41, 0
	global_load_dword v170, v210, s[40:41]
	s_add_u32 s40, s40, s71
	s_addc_u32 s41, s41, 0
	global_load_dword v171, v210, s[40:41]
	s_add_u32 s40, s40, s71
	s_addc_u32 s41, s41, 0
	global_load_dword v172, v210, s[40:41]
	s_add_u32 s40, s40, s71
	s_addc_u32 s41, s41, 0
	global_load_dword v173, v210, s[40:41]
	s_add_u32 s40, s40, s71
	s_addc_u32 s41, s41, 0
	global_load_dword v174, v210, s[40:41]
	s_add_u32 s40, s40, s71
	s_addc_u32 s41, s41, 0
	global_load_dword v175, v210, s[40:41]
	s_add_u32 s40, s40, s71
	s_addc_u32 s41, s41, 0
	global_load_dword v176, v210, s[40:41]
	s_add_u32 s40, s40, s71
	s_addc_u32 s41, s41, 0
	global_load_dword v177, v210, s[40:41]
	s_add_u32 s40, s40, s71
	s_addc_u32 s41, s41, 0
	global_load_dword v178, v210, s[40:41]
	s_add_u32 s40, s40, s71
	s_addc_u32 s41, s41, 0
	global_load_dword v179, v210, s[40:41]
	s_add_u32 s40, s40, s71
	s_addc_u32 s41, s41, 0
	global_load_dword v180, v210, s[40:41]
	s_add_u32 s40, s40, s71
	s_addc_u32 s41, s41, 0
	global_load_dword v181, v210, s[40:41]
	s_add_u32 s40, s40, s71
	s_addc_u32 s41, s41, 0
	global_load_dword v182, v210, s[40:41]
	s_add_u32 s40, s40, s71
	s_addc_u32 s41, s41, 0
	global_load_dword v183, v210, s[40:41]
	s_add_u32 s40, s40, s71
	s_addc_u32 s41, s41, 0
	global_load_dword v184, v210, s[40:41]
	s_add_u32 s40, s40, s71
	s_addc_u32 s41, s41, 0
	global_load_dword v185, v210, s[40:41]
	s_add_u32 s40, s40, s71
	s_addc_u32 s41, s41, 0
	global_load_dword v186, v210, s[40:41]
	s_add_u32 s40, s40, s71
	s_addc_u32 s41, s41, 0
	global_load_dword v187, v210, s[40:41]
	s_add_u32 s40, s40, s71
	s_addc_u32 s41, s41, 0
	global_load_dword v188, v210, s[40:41]
	s_add_u32 s40, s40, s71
	s_addc_u32 s41, s41, 0
	global_load_dword v189, v210, s[40:41]
	s_add_u32 s40, s40, s71
	s_addc_u32 s41, s41, 0
	global_load_dword v190, v210, s[40:41]
	s_add_u32 s40, s40, s71
	s_addc_u32 s41, s41, 0
	global_load_dword v191, v210, s[40:41]
	s_add_u32 s40, s40, s71
	s_addc_u32 s41, s41, 0
	global_load_dword v192, v210, s[40:41]
	s_add_u32 s40, s40, s71
	s_addc_u32 s41, s41, 0
	global_load_dword v193, v210, s[40:41]
	s_add_u32 s40, s40, s71
	s_addc_u32 s41, s41, 0
	global_load_dword v194, v210, s[40:41]
	s_add_u32 s40, s40, s71
	s_addc_u32 s41, s41, 0
	global_load_dword v195, v210, s[40:41]
	s_add_u32 s40, s40, s71
	s_addc_u32 s41, s41, 0
	global_load_dword v198, v210, s[40:41]
	s_add_u32 s40, s40, s71
	s_addc_u32 s41, s41, 0
	global_load_dword v199, v210, s[40:41]
	s_waitcnt vmcnt(31)
	ds_write_b32 v211, v166
	s_waitcnt vmcnt(30)
	ds_write_b32 v211, v167 offset:264
	s_waitcnt vmcnt(29)
	ds_write_b32 v211, v168 offset:528
	s_waitcnt vmcnt(28)
	ds_write_b32 v211, v169 offset:792
	s_waitcnt vmcnt(27)
	ds_write_b32 v211, v170 offset:1056
	s_waitcnt vmcnt(26)
	ds_write_b32 v211, v171 offset:1320
	s_waitcnt vmcnt(25)
	ds_write_b32 v211, v172 offset:1584
	s_waitcnt vmcnt(24)
	ds_write_b32 v211, v173 offset:1848
	s_waitcnt vmcnt(23)
	ds_write_b32 v211, v174 offset:2112
	s_waitcnt vmcnt(22)
	ds_write_b32 v211, v175 offset:2376
	s_waitcnt vmcnt(21)
	ds_write_b32 v211, v176 offset:2640
	s_waitcnt vmcnt(20)
	ds_write_b32 v211, v177 offset:2904
	s_waitcnt vmcnt(19)
	ds_write_b32 v211, v178 offset:3168
	s_waitcnt vmcnt(18)
	ds_write_b32 v211, v179 offset:3432
	s_waitcnt vmcnt(17)
	ds_write_b32 v211, v180 offset:3696
	s_waitcnt vmcnt(16)
	ds_write_b32 v211, v181 offset:3960
	s_waitcnt vmcnt(15)
	ds_write_b32 v211, v182 offset:4224
	s_waitcnt vmcnt(14)
	ds_write_b32 v211, v183 offset:4488
	s_waitcnt vmcnt(13)
	ds_write_b32 v211, v184 offset:4752
	s_waitcnt vmcnt(12)
	ds_write_b32 v211, v185 offset:5016
	s_waitcnt vmcnt(11)
	ds_write_b32 v211, v186 offset:5280
	s_waitcnt vmcnt(10)
	ds_write_b32 v211, v187 offset:5544
	s_waitcnt vmcnt(9)
	ds_write_b32 v211, v188 offset:5808
	s_waitcnt vmcnt(8)
	ds_write_b32 v211, v189 offset:6072
	s_waitcnt vmcnt(7)
	ds_write_b32 v211, v190 offset:6336
	s_waitcnt vmcnt(6)
	ds_write_b32 v211, v191 offset:6600
	s_waitcnt vmcnt(5)
	ds_write_b32 v211, v192 offset:6864
	s_waitcnt vmcnt(4)
	ds_write_b32 v211, v193 offset:7128
	s_waitcnt vmcnt(3)
	ds_write_b32 v211, v194 offset:7392
	s_waitcnt vmcnt(2)
	ds_write_b32 v211, v195 offset:7656
	s_waitcnt vmcnt(1)
	ds_write_b32 v211, v198 offset:7920
	s_waitcnt vmcnt(0)
	ds_write_b32 v211, v199 offset:8184
	s_add_u32 s9, s34, s4
	s_waitcnt lgkmcnt(0)
	s_addc_u32 s11, s35, s5
	s_add_i32 s10, s10, s25
	s_lshl_b64 s[4:5], s[6:7], 1
	s_add_u32 s6, s9, s4
	ds_read2_b32 v[166:167], v10 offset1:33
	ds_read2_b32 v[168:169], v10 offset0:66 offset1:99
	ds_read2_b32 v[170:171], v10 offset0:132 offset1:165
	ds_read2_b32 v[172:173], v10 offset0:198 offset1:231
	ds_read2_b32 v[174:175], v10 offset0:8 offset1:41
	ds_read2_b32 v[176:177], v10 offset0:74 offset1:107
	ds_read2_b32 v[178:179], v10 offset0:140 offset1:173
	ds_read2_b32 v[180:181], v10 offset0:206 offset1:239
	ds_read2_b32 v[182:183], v10 offset0:16 offset1:49
	ds_read2_b32 v[184:185], v10 offset0:82 offset1:115
	ds_read2_b32 v[186:187], v10 offset0:148 offset1:181
	ds_read2_b32 v[188:189], v10 offset0:214 offset1:247
	ds_read2_b32 v[190:191], v10 offset0:24 offset1:57
	ds_read2_b32 v[192:193], v10 offset0:90 offset1:123
	ds_read2_b32 v[194:195], v10 offset0:156 offset1:189
	ds_read2_b32 v[198:199], v10 offset0:222 offset1:255
	s_addc_u32 s7, s11, s5
	s_ashr_i32 s9, s8, 31
	s_waitcnt lgkmcnt(12)
	v_cvt_pk_bf16_f32 v14, v166, v167
	s_lshl_b64 s[4:5], s[8:9], 1
	s_waitcnt lgkmcnt(12)
	v_cvt_pk_bf16_f32 v15, v168, v169
	v_add_u32_e32 v18, s10, v5
	s_add_u32 s4, s6, s4
	v_ashrrev_i32_e32 v19, 31, v18
	s_waitcnt lgkmcnt(12)
	v_cvt_pk_bf16_f32 v16, v170, v171
	s_addc_u32 s5, s7, s5
	v_lshl_add_u64 v[20:21], s[4:5], 0, v[2:3]
	s_waitcnt lgkmcnt(12)
	v_cvt_pk_bf16_f32 v17, v172, v173
	v_lshlrev_b64 v[8:9], 12, v[18:19]
	v_lshl_add_u64 v[8:9], v[20:21], 0, v[8:9]
	global_store_dwordx4 v[8:9], v[14:17], off
	s_nop 1
	v_add_u32_e32 v18, s10, v11
	v_ashrrev_i32_e32 v19, 31, v18
	s_waitcnt lgkmcnt(8)
	v_cvt_pk_bf16_f32 v14, v174, v175
	v_lshlrev_b64 v[18:19], 12, v[18:19]
	s_waitcnt lgkmcnt(8)
	v_cvt_pk_bf16_f32 v15, v176, v177
	v_lshl_add_u64 v[18:19], v[20:21], 0, v[18:19]
	s_waitcnt lgkmcnt(8)
	v_cvt_pk_bf16_f32 v16, v178, v179
	s_waitcnt lgkmcnt(8)
	v_cvt_pk_bf16_f32 v17, v180, v181
	global_store_dwordx4 v[18:19], v[14:17], off
	s_nop 1
	v_add_u32_e32 v18, s10, v12
	v_ashrrev_i32_e32 v19, 31, v18
	s_waitcnt lgkmcnt(4)
	v_cvt_pk_bf16_f32 v14, v182, v183
	v_lshlrev_b64 v[18:19], 12, v[18:19]
	s_waitcnt lgkmcnt(4)
	v_cvt_pk_bf16_f32 v15, v184, v185
	v_lshl_add_u64 v[18:19], v[20:21], 0, v[18:19]
	s_waitcnt lgkmcnt(4)
	v_cvt_pk_bf16_f32 v16, v186, v187
	s_waitcnt lgkmcnt(4)
	v_cvt_pk_bf16_f32 v17, v188, v189
	global_store_dwordx4 v[18:19], v[14:17], off
	s_nop 1
	v_add_u32_e32 v18, s10, v13
	v_ashrrev_i32_e32 v19, 31, v18
	s_waitcnt lgkmcnt(0)
	v_cvt_pk_bf16_f32 v14, v190, v191
	v_lshlrev_b64 v[18:19], 12, v[18:19]
	s_waitcnt lgkmcnt(0)
	v_cvt_pk_bf16_f32 v15, v192, v193
	v_lshl_add_u64 v[18:19], v[20:21], 0, v[18:19]
	s_waitcnt lgkmcnt(0)
	v_cvt_pk_bf16_f32 v16, v194, v195
	s_waitcnt lgkmcnt(0)
	v_cvt_pk_bf16_f32 v17, v198, v199
	global_store_dwordx4 v[18:19], v[14:17], off
	s_nop 1
	s_waitcnt lgkmcnt(0)
	s_add_i32 s3, s3, s14
	s_cmpk_lt_i32 s3, 0x7400
	s_cbranch_scc1 .LBB0_454

.LBB0_1151:
	s_ashr_i32 s13, s12, 31
	s_lshl_b64 s[12:13], s[12:13], 3
	s_add_u32 s14, s0, s12
	s_addc_u32 s15, s1, s13
	s_lshr_b32 s12, s29, 5
	v_cvt_f32_u32_e32 v8, s12
	s_load_dwordx2 s[40:41], s[14:15], 0x0
	s_sub_i32 s14, 0, s12
	s_abs_i32 s46, s36
	v_rcp_iflag_f32_e32 v8, v8
	s_ashr_i32 s45, s36, 31
	s_mov_b32 s13, 0
	s_mov_b32 s44, 1
	v_mul_f32_e32 v8, 0x4f7ffffe, v8
	v_cvt_u32_f32_e32 v8, v8
	s_nop 0
	v_readfirstlane_b32 s15, v8
	s_mul_i32 s14, s14, s15
	s_mul_hi_u32 s14, s15, s14
	s_add_i32 s15, s15, s14
	s_mul_hi_u32 s14, s46, s15
	s_mul_i32 s15, s14, s12
	s_sub_i32 s15, s46, s15
	s_add_i32 s47, s14, 1
	s_sub_i32 s46, s15, s12
	s_cmp_ge_u32 s15, s12
	s_cselect_b32 s14, s47, s14
	s_cselect_b32 s15, s46, s15
	s_add_i32 s46, s14, 1
	s_cmp_ge_u32 s15, s12
	s_cselect_b32 s14, s46, s14
	s_xor_b32 s14, s14, s45
	s_sub_i32 s14, s14, s45
	s_mul_i32 s12, s14, s12
	s_sub_i32 s15, s36, s12
	s_lshl_b32 s12, s14, 6
	s_lshl_b32 s14, s15, 5
	s_ashr_i32 s15, s14, 31
	s_lshl_b64 s[46:47], s[14:15], 2
	s_waitcnt lgkmcnt(0)
	s_add_u32 s40, s40, s46
	s_addc_u32 s41, s41, s47
	s_mul_i32 s70, s12, s29
	s_lshl_b32 s71, s29, 2
	s_lshl_b32 s70, s70, 2
	s_add_u32 s40, s40, s70
	s_addc_u32 s41, s41, 0
	v_mad_u32_u24 v210, v0, s71, v6
	v_mad_u32_u24 v211, v0, s25, v4
	s_lshl_b32 s71, s71, 1
	global_load_dword v166, v210, s[40:41]
	s_add_u32 s40, s40, s71
	s_addc_u32 s41, s41, 0
	global_load_dword v167, v210, s[40:41]
	s_add_u32 s40, s40, s71
	s_addc_u32 s41, s41, 0
	global_load_dword v168, v210, s[40:41]
	s_add_u32 s40, s40, s71
	s_addc_u32 s41, s41, 0
	global_load_dword v169, v210, s[40:41]
	s_add_u32 s40, s40, s71
	s_addc_u32 s41, s41, 0
	global_load_dword v170, v210, s[40:41]
	s_add_u32 s40, s40, s71
	s_addc_u32 s41, s41, 0
	global_load_dword v171, v210, s[40:41]
	s_add_u32 s40, s40, s71
	s_addc_u32 s41, s41, 0
	global_load_dword v172, v210, s[40:41]
	s_add_u32 s40, s40, s71
	s_addc_u32 s41, s41, 0
	global_load_dword v173, v210, s[40:41]
	s_add_u32 s40, s40, s71
	s_addc_u32 s41, s41, 0
	global_load_dword v174, v210, s[40:41]
	s_add_u32 s40, s40, s71
	s_addc_u32 s41, s41, 0
	global_load_dword v175, v210, s[40:41]
	s_add_u32 s40, s40, s71
	s_addc_u32 s41, s41, 0
	global_load_dword v176, v210, s[40:41]
	s_add_u32 s40, s40, s71
	s_addc_u32 s41, s41, 0
	global_load_dword v177, v210, s[40:41]
	s_add_u32 s40, s40, s71
	s_addc_u32 s41, s41, 0
	global_load_dword v178, v210, s[40:41]
	s_add_u32 s40, s40, s71
	s_addc_u32 s41, s41, 0
	global_load_dword v179, v210, s[40:41]
	s_add_u32 s40, s40, s71
	s_addc_u32 s41, s41, 0
	global_load_dword v180, v210, s[40:41]
	s_add_u32 s40, s40, s71
	s_addc_u32 s41, s41, 0
	global_load_dword v181, v210, s[40:41]
	s_add_u32 s40, s40, s71
	s_addc_u32 s41, s41, 0
	global_load_dword v182, v210, s[40:41]
	s_add_u32 s40, s40, s71
	s_addc_u32 s41, s41, 0
	global_load_dword v183, v210, s[40:41]
	s_add_u32 s40, s40, s71
	s_addc_u32 s41, s41, 0
	global_load_dword v184, v210, s[40:41]
	s_add_u32 s40, s40, s71
	s_addc_u32 s41, s41, 0
	global_load_dword v185, v210, s[40:41]
	s_add_u32 s40, s40, s71
	s_addc_u32 s41, s41, 0
	global_load_dword v186, v210, s[40:41]
	s_add_u32 s40, s40, s71
	s_addc_u32 s41, s41, 0
	global_load_dword v187, v210, s[40:41]
	s_add_u32 s40, s40, s71
	s_addc_u32 s41, s41, 0
	global_load_dword v188, v210, s[40:41]
	s_add_u32 s40, s40, s71
	s_addc_u32 s41, s41, 0
	global_load_dword v189, v210, s[40:41]
	s_add_u32 s40, s40, s71
	s_addc_u32 s41, s41, 0
	global_load_dword v190, v210, s[40:41]
	s_add_u32 s40, s40, s71
	s_addc_u32 s41, s41, 0
	global_load_dword v191, v210, s[40:41]
	s_add_u32 s40, s40, s71
	s_addc_u32 s41, s41, 0
	global_load_dword v192, v210, s[40:41]
	s_add_u32 s40, s40, s71
	s_addc_u32 s41, s41, 0
	global_load_dword v193, v210, s[40:41]
	s_add_u32 s40, s40, s71
	s_addc_u32 s41, s41, 0
	global_load_dword v194, v210, s[40:41]
	s_add_u32 s40, s40, s71
	s_addc_u32 s41, s41, 0
	global_load_dword v195, v210, s[40:41]
	s_add_u32 s40, s40, s71
	s_addc_u32 s41, s41, 0
	global_load_dword v198, v210, s[40:41]
	s_add_u32 s40, s40, s71
	s_addc_u32 s41, s41, 0
	global_load_dword v199, v210, s[40:41]
	s_waitcnt vmcnt(31)
	ds_write_b32 v211, v166
	s_waitcnt vmcnt(30)
	ds_write_b32 v211, v167 offset:264
	s_waitcnt vmcnt(29)
	ds_write_b32 v211, v168 offset:528
	s_waitcnt vmcnt(28)
	ds_write_b32 v211, v169 offset:792
	s_waitcnt vmcnt(27)
	ds_write_b32 v211, v170 offset:1056
	s_waitcnt vmcnt(26)
	ds_write_b32 v211, v171 offset:1320
	s_waitcnt vmcnt(25)
	ds_write_b32 v211, v172 offset:1584
	s_waitcnt vmcnt(24)
	ds_write_b32 v211, v173 offset:1848
	s_waitcnt vmcnt(23)
	ds_write_b32 v211, v174 offset:2112
	s_waitcnt vmcnt(22)
	ds_write_b32 v211, v175 offset:2376
	s_waitcnt vmcnt(21)
	ds_write_b32 v211, v176 offset:2640
	s_waitcnt vmcnt(20)
	ds_write_b32 v211, v177 offset:2904
	s_waitcnt vmcnt(19)
	ds_write_b32 v211, v178 offset:3168
	s_waitcnt vmcnt(18)
	ds_write_b32 v211, v179 offset:3432
	s_waitcnt vmcnt(17)
	ds_write_b32 v211, v180 offset:3696
	s_waitcnt vmcnt(16)
	ds_write_b32 v211, v181 offset:3960
	s_waitcnt vmcnt(15)
	ds_write_b32 v211, v182 offset:4224
	s_waitcnt vmcnt(14)
	ds_write_b32 v211, v183 offset:4488
	s_waitcnt vmcnt(13)
	ds_write_b32 v211, v184 offset:4752
	s_waitcnt vmcnt(12)
	ds_write_b32 v211, v185 offset:5016
	s_waitcnt vmcnt(11)
	ds_write_b32 v211, v186 offset:5280
	s_waitcnt vmcnt(10)
	ds_write_b32 v211, v187 offset:5544
	s_waitcnt vmcnt(9)
	ds_write_b32 v211, v188 offset:5808
	s_waitcnt vmcnt(8)
	ds_write_b32 v211, v189 offset:6072
	s_waitcnt vmcnt(7)
	ds_write_b32 v211, v190 offset:6336
	s_waitcnt vmcnt(6)
	ds_write_b32 v211, v191 offset:6600
	s_waitcnt vmcnt(5)
	ds_write_b32 v211, v192 offset:6864
	s_waitcnt vmcnt(4)
	ds_write_b32 v211, v193 offset:7128
	s_waitcnt vmcnt(3)
	ds_write_b32 v211, v194 offset:7392
	s_waitcnt vmcnt(2)
	ds_write_b32 v211, v195 offset:7656
	s_waitcnt vmcnt(1)
	ds_write_b32 v211, v198 offset:7920
	s_waitcnt vmcnt(0)
	ds_write_b32 v211, v199 offset:8184
	s_add_u32 s13, s34, s8
	s_waitcnt lgkmcnt(0)
	s_addc_u32 s15, s35, s9
	s_add_i32 s14, s14, s37
	s_lshl_b64 s[8:9], s[10:11], 1
	s_add_u32 s10, s13, s8
	ds_read2_b32 v[166:167], v10 offset1:33
	ds_read2_b32 v[168:169], v10 offset0:66 offset1:99
	ds_read2_b32 v[170:171], v10 offset0:132 offset1:165
	ds_read2_b32 v[172:173], v10 offset0:198 offset1:231
	ds_read2_b32 v[174:175], v10 offset0:8 offset1:41
	ds_read2_b32 v[176:177], v10 offset0:74 offset1:107
	ds_read2_b32 v[178:179], v10 offset0:140 offset1:173
	ds_read2_b32 v[180:181], v10 offset0:206 offset1:239
	ds_read2_b32 v[182:183], v10 offset0:16 offset1:49
	ds_read2_b32 v[184:185], v10 offset0:82 offset1:115
	ds_read2_b32 v[186:187], v10 offset0:148 offset1:181
	ds_read2_b32 v[188:189], v10 offset0:214 offset1:247
	ds_read2_b32 v[190:191], v10 offset0:24 offset1:57
	ds_read2_b32 v[192:193], v10 offset0:90 offset1:123
	ds_read2_b32 v[194:195], v10 offset0:156 offset1:189
	ds_read2_b32 v[198:199], v10 offset0:222 offset1:255
	s_addc_u32 s11, s15, s9
	s_ashr_i32 s13, s12, 31
	s_waitcnt lgkmcnt(12)
	v_cvt_pk_bf16_f32 v14, v166, v167
	s_lshl_b64 s[8:9], s[12:13], 1
	s_waitcnt lgkmcnt(12)
	v_cvt_pk_bf16_f32 v15, v168, v169
	v_add_u32_e32 v20, s14, v5
	s_add_u32 s8, s10, s8
	v_ashrrev_i32_e32 v21, 31, v20
	s_waitcnt lgkmcnt(12)
	v_cvt_pk_bf16_f32 v16, v170, v171
	s_addc_u32 s9, s11, s9
	v_lshl_add_u64 v[18:19], s[8:9], 0, v[2:3]
	s_waitcnt lgkmcnt(12)
	v_cvt_pk_bf16_f32 v17, v172, v173
	v_mul_lo_u32 v21, s6, v21
	v_mul_lo_u32 v22, s7, v20
	v_mad_u64_u32 v[8:9], s[8:9], s6, v20, 0
	v_add3_u32 v9, v9, v21, v22
	v_lshl_add_u64 v[8:9], v[8:9], 1, v[18:19]
	global_store_dwordx4 v[8:9], v[14:17], off
	s_nop 1
	s_add_i32 s3, s3, s19
	v_add_u32_e32 v17, s14, v11
	s_waitcnt lgkmcnt(8)
	v_cvt_pk_bf16_f32 v14, v174, v175
	v_ashrrev_i32_e32 v22, 31, v17
	s_waitcnt lgkmcnt(8)
	v_cvt_pk_bf16_f32 v15, v176, v177
	v_mul_lo_u32 v23, s7, v17
	v_mad_u64_u32 v[20:21], s[8:9], s6, v17, 0
	v_mul_lo_u32 v17, s6, v22
	s_waitcnt lgkmcnt(8)
	v_cvt_pk_bf16_f32 v16, v178, v179
	v_add3_u32 v21, v21, v17, v23
	s_waitcnt lgkmcnt(8)
	v_cvt_pk_bf16_f32 v17, v180, v181
	v_lshl_add_u64 v[8:9], v[20:21], 1, v[18:19]
	global_store_dwordx4 v[8:9], v[14:17], off
	s_nop 1
	s_cmp_lt_i32 s3, 0x9400
	v_add_u32_e32 v17, s14, v12
	v_ashrrev_i32_e32 v22, 31, v17
	v_mul_lo_u32 v23, s7, v17
	v_mad_u64_u32 v[20:21], s[8:9], s6, v17, 0
	v_mul_lo_u32 v17, s6, v22
	s_waitcnt lgkmcnt(4)
	v_cvt_pk_bf16_f32 v14, v182, v183
	v_add3_u32 v21, v21, v17, v23
	s_waitcnt lgkmcnt(4)
	v_cvt_pk_bf16_f32 v15, v184, v185
	s_waitcnt lgkmcnt(4)
	v_cvt_pk_bf16_f32 v16, v186, v187
	v_lshl_add_u64 v[20:21], v[20:21], 1, v[18:19]
	s_waitcnt lgkmcnt(4)
	v_cvt_pk_bf16_f32 v17, v188, v189
	global_store_dwordx4 v[20:21], v[14:17], off
	s_nop 1
	s_nop 0
	v_add_u32_e32 v16, s14, v13
	v_ashrrev_i32_e32 v17, 31, v16
	v_mul_lo_u32 v22, s7, v16
	v_mad_u64_u32 v[20:21], s[8:9], s6, v16, 0
	v_mul_lo_u32 v17, s6, v17
	s_waitcnt lgkmcnt(0)
	v_cvt_pk_bf16_f32 v14, v190, v191
	v_add3_u32 v21, v21, v17, v22
	s_waitcnt lgkmcnt(0)
	v_cvt_pk_bf16_f32 v15, v192, v193
	v_lshl_add_u64 v[18:19], v[20:21], 1, v[18:19]
	s_waitcnt lgkmcnt(0)
	v_cvt_pk_bf16_f32 v16, v194, v195
	s_waitcnt lgkmcnt(0)
	v_cvt_pk_bf16_f32 v17, v198, v199
	global_store_dwordx4 v[18:19], v[14:17], off
	s_nop 1
	s_waitcnt lgkmcnt(0)
	s_cbranch_scc1 .LBB0_1111
